# speedup vs baseline: 1.0299x; 1.0022x over previous
; #define SBAR() __builtin_amdgcn_sched_barrier(0)
; __device__ __forceinline__ void finishSM(f32x16& p0, f32x16& p1, float alpha, float& l_reg, bf16x8& pa0, bf16x8& pa1, bf16x8& pa2, bf16x8& pa3) {
; #pragma unroll
;   for (int r = 0; r < 16; ++r) p1[r] = __builtin_amdgcn_exp2f(p1[r]);
;   float ps = 0;
; #pragma unroll
;   for (int r = 0; r < 16; ++r) ps += p0[r];
; #pragma unroll
;   for (int r = 0; r < 16; ++r) ps += p1[r];
;   { auto rr = __builtin_amdgcn_permlane32_swap(__float_as_uint(ps), __float_as_uint(ps), false, false);
;     ps = __uint_as_float(rr[0]) + __uint_as_float(rr[1]); }
;   l_reg = l_reg * alpha + ps;
;     ...
;   PK4(p0, 0, pa0); PK4(p0, 8, pa1); PK4(p1, 0, pa2); PK4(p1, 8, pa3);
;     ...
; }
; template <int D0> __device__ __forceinline__ void pv_one_t(f32x16& od, int vb, bf16x8 pa0, bf16x8 pa1, bf16x8 pa2, bf16x8 pa3) {
;   const s16x4 l0 = tr_read<v_rd_off(D0, 0, 0)>(vb), h0 = tr_read<v_rd_off(D0, 0, 1)>(vb), l1 = tr_read<v_rd_off(D0, 1, 0)>(vb), h1 = tr_read<v_rd_off(D0, 1, 1)>(vb);
;   const s16x4 l2 = tr_read<v_rd_off(D0, 2, 0)>(vb), h2 = tr_read<v_rd_off(D0, 2, 1)>(vb), l3 = tr_read<v_rd_off(D0, 3, 0)>(vb), h3 = tr_read<v_rd_off(D0, 3, 1)>(vb);
;   asm volatile("s_waitcnt lgkmcnt(0)" ::: "memory"); SBAR();
;     ...
;   od = __builtin_amdgcn_mfma_f32_32x32x16_bf16(PK(l0, h0), pa0, od, 0, 0, 0);
;   od = __builtin_amdgcn_mfma_f32_32x32x16_bf16(PK(l1, h1), pa1, od, 0, 0, 0);
;   od = __builtin_amdgcn_mfma_f32_32x32x16_bf16(PK(l2, h2), pa2, od, 0, 0, 0);
;   od = __builtin_amdgcn_mfma_f32_32x32x16_bf16(PK(l3, h3), pa3, od, 0, 0, 0);
;     ...
; }
.LBB0_113:
	v_cndmask_b32_e64 v97, v97, v197, s[4:5]
	v_mul_f32_e32 v97, 0xbdd53b94, v97
	v_fmamk_f32 v80, v80, 0x3dd53b94, v97
	v_fmamk_f32 v81, v81, 0x3dd53b94, v97
	v_exp_f32_e32 v80, v80
	v_fmamk_f32 v82, v82, 0x3dd53b94, v97
	v_exp_f32_e32 v81, v81
	v_fmamk_f32 v83, v83, 0x3dd53b94, v97
	v_exp_f32_e32 v82, v82
	v_fmamk_f32 v84, v84, 0x3dd53b94, v97
	v_exp_f32_e32 v83, v83
	v_fmamk_f32 v65, v65, 0x3dd53b94, v97
	v_fmamk_f32 v85, v85, 0x3dd53b94, v97
	v_exp_f32_e32 v84, v84
	v_exp_f32_e32 v99, v65
	v_add_f32_e32 v65, 0, v80
	v_fmamk_f32 v86, v86, 0x3dd53b94, v97
	v_exp_f32_e32 v85, v85
	v_add_f32_e32 v65, v81, v65
	v_fmamk_f32 v87, v87, 0x3dd53b94, v97
	v_exp_f32_e32 v86, v86
	v_add_f32_e32 v65, v82, v65
	v_fmamk_f32 v88, v88, 0x3dd53b94, v97
	v_exp_f32_e32 v87, v87
	v_add_f32_e32 v65, v83, v65
	v_fmamk_f32 v89, v89, 0x3dd53b94, v97
	v_exp_f32_e32 v88, v88
	v_add_f32_e32 v65, v84, v65
	v_fmamk_f32 v90, v90, 0x3dd53b94, v97
	v_exp_f32_e32 v89, v89
	v_add_f32_e32 v65, v85, v65
	v_fmamk_f32 v91, v91, 0x3dd53b94, v97
	v_exp_f32_e32 v90, v90
	v_add_f32_e32 v65, v86, v65
	v_fmamk_f32 v92, v92, 0x3dd53b94, v97
	v_exp_f32_e32 v91, v91
	v_add_f32_e32 v65, v87, v65
	v_fmamk_f32 v93, v93, 0x3dd53b94, v97
	v_exp_f32_e32 v92, v92
	v_add_f32_e32 v65, v88, v65
	v_fmamk_f32 v94, v94, 0x3dd53b94, v97
	v_exp_f32_e32 v93, v93
	v_add_f32_e32 v65, v89, v65
	v_fmamk_f32 v95, v95, 0x3dd53b94, v97
	v_exp_f32_e32 v94, v94
	v_add_f32_e32 v65, v90, v65
	v_exp_f32_e32 v95, v95
	v_fmamk_f32 v79, v79, 0x3dd53b94, v97
	v_fmamk_f32 v78, v78, 0x3dd53b94, v97
	v_fmamk_f32 v77, v77, 0x3dd53b94, v97
	v_fmamk_f32 v76, v76, 0x3dd53b94, v97
	v_fmamk_f32 v75, v75, 0x3dd53b94, v97
	v_fmamk_f32 v74, v74, 0x3dd53b94, v97
	v_fmamk_f32 v73, v73, 0x3dd53b94, v97
	v_fmamk_f32 v72, v72, 0x3dd53b94, v97
	v_fmamk_f32 v71, v71, 0x3dd53b94, v97
	v_fmamk_f32 v70, v70, 0x3dd53b94, v97
	v_fmamk_f32 v69, v69, 0x3dd53b94, v97
	v_fmamk_f32 v68, v68, 0x3dd53b94, v97
	v_fmamk_f32 v67, v67, 0x3dd53b94, v97
	v_fmamk_f32 v98, v66, 0x3dd53b94, v97
	v_fmac_f32_e32 v97, 0x3dd53b94, v64
	v_add_f32_e32 v65, v91, v65
	v_exp_f32_e32 v97, v97
	v_add_f32_e32 v65, v92, v65
	v_add_f32_e32 v65, v93, v65
	v_exp_f32_e32 v98, v98
	v_add_f32_e32 v65, v94, v65
	v_add_f32_e32 v66, v100, v101
	v_exp_f32_e32 v100, v67
	v_add_f32_e32 v65, v95, v65
	v_exp_f32_e32 v101, v68
	v_add_f32_e32 v65, v97, v65
	v_exp_f32_e32 v102, v69
	v_add_f32_e32 v65, v99, v65
	v_exp_f32_e32 v103, v70
	v_add_f32_e32 v65, v98, v65
	v_exp_f32_e32 v104, v71
	v_add_f32_e32 v65, v100, v65
	v_exp_f32_e32 v105, v72
	v_add_f32_e32 v65, v101, v65
	v_exp_f32_e32 v106, v73
	v_add_f32_e32 v65, v102, v65
	v_exp_f32_e32 v107, v74
	v_add_f32_e32 v65, v103, v65
	v_exp_f32_e32 v108, v75
	v_add_f32_e32 v65, v104, v65
	v_exp_f32_e32 v109, v76
	v_add_f32_e32 v65, v105, v65
	v_exp_f32_e32 v110, v77
	v_add_f32_e32 v65, v106, v65
	v_exp_f32_e32 v111, v78
	v_add_f32_e32 v65, v107, v65
	v_exp_f32_e32 v112, v79
	v_add_f32_e32 v65, v108, v65
	v_add_f32_e32 v65, v109, v65
	v_add_f32_e32 v65, v110, v65
	v_add_f32_e32 v65, v111, v65
	s_lshl_b64 s[12:13], s[12:13], 11
	v_add_f32_e32 v65, v112, v65
	s_add_u32 s12, s28, s12
	v_mov_b32_e32 v67, v65
	s_addc_u32 s13, s29, s13
	s_lshl_b32 s14, s37, 1
	v_mul_f32_e32 v64, v162, v144
	v_permlane32_swap_b32_e32 v65, v67
	s_add_u32 s12, s12, s14
	v_pk_add_f32 v[64:65], v[64:65], v[66:67]
	v_cvt_pk_bf16_f32 v66, v80, v81
	v_cvt_pk_bf16_f32 v67, v82, v83
	v_cvt_pk_bf16_f32 v68, v84, v85
	v_cvt_pk_bf16_f32 v69, v86, v87
	v_cvt_pk_bf16_f32 v70, v88, v89
	v_cvt_pk_bf16_f32 v71, v90, v91
	v_cvt_pk_bf16_f32 v72, v92, v93
	v_cvt_pk_bf16_f32 v73, v94, v95
	v_cvt_pk_bf16_f32 v74, v97, v99
	v_cvt_pk_bf16_f32 v75, v98, v100
	v_cvt_pk_bf16_f32 v76, v101, v102
	v_cvt_pk_bf16_f32 v77, v103, v104
	v_cvt_pk_bf16_f32 v78, v105, v106
	v_cvt_pk_bf16_f32 v79, v107, v108
	v_cvt_pk_bf16_f32 v80, v109, v110
	v_cvt_pk_bf16_f32 v81, v111, v112
	s_addc_u32 s13, s13, 0
	v_fmac_f32_e32 v65, v64, v96
	ds_read_b64_tr_b16 v[82:83], v196 offset:0
	ds_read_b64_tr_b16 v[84:85], v196 offset:0x800
	ds_read_b64_tr_b16 v[86:87], v196 offset:0x1000
	ds_read_b64_tr_b16 v[88:89], v196 offset:0x1800
	ds_read_b64_tr_b16 v[90:91], v196 offset:0x2000
	ds_read_b64_tr_b16 v[92:93], v196 offset:0x2800
	ds_read_b64_tr_b16 v[94:95], v196 offset:0x3000
	ds_read_b64_tr_b16 v[96:97], v196 offset:0x3800
	s_waitcnt lgkmcnt(0)
	s_nop 0
	v_mfma_f32_32x32x16_bf16 v[0:15], v[82:85], v[66:69], v[0:15]
	ds_read_b64_tr_b16 v[82:83], v196 offset:0x200
	ds_read_b64_tr_b16 v[84:85], v196 offset:0xa00
	v_mfma_f32_32x32x16_bf16 v[0:15], v[86:89], v[70:73], v[0:15]
	ds_read_b64_tr_b16 v[86:87], v196 offset:0x1200
	ds_read_b64_tr_b16 v[88:89], v196 offset:0x1a00
	v_mfma_f32_32x32x16_bf16 v[0:15], v[90:93], v[74:77], v[0:15]
	ds_read_b64_tr_b16 v[90:91], v196 offset:0x2200
	ds_read_b64_tr_b16 v[92:93], v196 offset:0x2a00
	v_mfma_f32_32x32x16_bf16 v[0:15], v[94:97], v[78:81], v[0:15]
	ds_read_b64_tr_b16 v[94:95], v196 offset:0x3200
	ds_read_b64_tr_b16 v[96:97], v196 offset:0x3a00
	s_waitcnt lgkmcnt(0)
	v_mfma_f32_32x32x16_bf16 v[48:63], v[82:85], v[66:69], v[48:63]
	ds_read_b64_tr_b16 v[82:83], v196 offset:0x400
	ds_read_b64_tr_b16 v[84:85], v196 offset:0xc00
	v_mfma_f32_32x32x16_bf16 v[48:63], v[86:89], v[70:73], v[48:63]
	ds_read_b64_tr_b16 v[86:87], v196 offset:0x1400
	ds_read_b64_tr_b16 v[88:89], v196 offset:0x1c00
	v_mfma_f32_32x32x16_bf16 v[48:63], v[90:93], v[74:77], v[48:63]
	ds_read_b64_tr_b16 v[90:91], v196 offset:0x2400
	ds_read_b64_tr_b16 v[92:93], v196 offset:0x2c00
	v_mfma_f32_32x32x16_bf16 v[48:63], v[94:97], v[78:81], v[48:63]
	ds_read_b64_tr_b16 v[94:95], v196 offset:0x3400
	ds_read_b64_tr_b16 v[96:97], v196 offset:0x3c00
	s_waitcnt lgkmcnt(0)
; #define SBAR() __builtin_amdgcn_sched_barrier(0)
; #define RESC(a) do { if (__any((a) < 1.f)) { if (hi == 0) al_l[r32] = (a); asm volatile("s_waitcnt lgkmcnt(0)" ::: "memory"); \
;     for (int d = 0; d < 4; ++d) for (int r = 0; r < 16; ++r) o[d][r] *= al_l[crow_(r, hi)]; } } while (0)
; #define RESC(a) do { if (__any((a) < 1.f)) { for (int d = 0; d < 4; ++d) for (int r = 0; r < 16; ++r) o[d][r] *= (a); } } while (0)
; #define RESC(a) do { if (__any((a) < 1.f)) { for (int d = 0; d < 4; ++d) for (int r = 0; r < 16; ++r) o[d][r] *= (a); } } while (0)
; __device__ __forceinline__ void attn_mla_dma(const bf16_t* __restrict__ Qb, const bf16_t* __restrict__ Kh, const bf16_t* __restrict__ Vh, bf16_t* __restrict__ Ob,
;                                              int seq, char* lds, const int tid) {
;     ...
;   SBAR(); qkt_mla<(int)SHM_K192>(pB0, pB1, ka, qr, qlds);
;   finishSM(pA0, pA1, alA, l_reg, pa0, pa1, pa2, pa3); SBAR();
;   pv_d0_t(o, vb0 + vprev * SHM_VV, pa0, pa1, pa2, pa3); partialSM<MLA>(pB0, pB1, m_reg, mnB, alB);
;   RESC(alB);
;   finishSM(pB0, pB1, alB, l_reg, pa0, pa1, pa2, pa3); SBAR();
;   pv_d0_t(o, vb0 + vcur * SHM_VV, pa0, pa1, pa2, pa3);
;   int tide = tid; asm volatile("" : "+v"(tide));
;   const int wide = tide >> 6, r32e = tide & 31, hie = (tide >> 5) & 1;
;   const float rl = __builtin_amdgcn_rcpf(l_reg);
;   bf16_t* Ow = Ob + (long)(wide * QBLK + r32e) * LDO + hie * 8;
; #pragma unroll
;   for (int d0 = 0; d0 < 4; ++d0)
; #pragma unroll
;     for (int b = 0; b < 16; b += 8) {
;       const u32x4 w = pack8_row(o[d0][b] * rl, o[d0][b + 1] * rl, o[d0][b + 2] * rl, o[d0][b + 3] * rl, o[d0][b + 4] * rl, o[d0][b + 5] * rl, o[d0][b + 6] * rl, o[d0][b + 7] * rl);
;       *reinterpret_cast<u32x4*>(Ow + d0 * 32 + b * 2) = w;
;     }
;   __syncthreads();
	v_mfma_f32_32x32x16_bf16 v[32:47], v[82:85], v[66:69], v[32:47]
	ds_read_b64_tr_b16 v[82:83], v196 offset:0x600
	ds_read_b64_tr_b16 v[84:85], v196 offset:0xe00
	v_mfma_f32_32x32x16_bf16 v[32:47], v[86:89], v[70:73], v[32:47]
	ds_read_b64_tr_b16 v[86:87], v196 offset:0x1600
	ds_read_b64_tr_b16 v[88:89], v196 offset:0x1e00
	v_mfma_f32_32x32x16_bf16 v[32:47], v[90:93], v[74:77], v[32:47]
	ds_read_b64_tr_b16 v[90:91], v196 offset:0x2600
	ds_read_b64_tr_b16 v[92:93], v196 offset:0x2e00
	v_mfma_f32_32x32x16_bf16 v[32:47], v[94:97], v[78:81], v[32:47]
	ds_read_b64_tr_b16 v[94:95], v196 offset:0x3600
	ds_read_b64_tr_b16 v[96:97], v196 offset:0x3e00
	s_waitcnt lgkmcnt(0)
	v_mfma_f32_32x32x16_bf16 v[16:31], v[82:85], v[66:69], v[16:31]
	v_rcp_f32_e32 v66, v65
	s_movk_i32 s4, 0xffe0
	v_ashrrev_i32_e32 v64, 1, v156
	v_bfi_b32 v64, s4, v64, v156
	v_ashrrev_i32_e32 v65, 31, v64
	v_lshlrev_b64 v[64:65], 11, v[64:65]
	v_mfma_f32_32x32x16_bf16 v[16:31], v[86:89], v[70:73], v[16:31]
	v_lshrrev_b32_e32 v67, 1, v156
	v_mul_f32_e32 v0, v66, v0
	v_mul_f32_e32 v1, v66, v1
	v_mul_f32_e32 v2, v66, v2
	v_mul_f32_e32 v3, v66, v3
	v_lshl_add_u64 v[64:65], s[12:13], 0, v[64:65]
	v_and_b32_e32 v162, 16, v67
	v_mul_f32_e32 v4, v66, v4
	v_mul_f32_e32 v5, v66, v5
	v_mul_f32_e32 v6, v66, v6
	v_mul_f32_e32 v7, v66, v7
	v_cvt_pk_bf16_f32 v0, v0, v1
	v_cvt_pk_bf16_f32 v1, v2, v3
	v_cvt_pk_bf16_f32 v2, v4, v5
	v_cvt_pk_bf16_f32 v3, v6, v7
	v_mfma_f32_32x32x16_bf16 v[16:31], v[90:93], v[74:77], v[16:31]
	v_lshl_add_u64 v[64:65], v[64:65], 0, v[162:163]
	v_permlane32_swap_b32_e32 v0, v2
	v_permlane32_swap_b32_e32 v1, v3
	flat_store_dwordx4 v[64:65], v[0:3]
	v_mul_f32_e32 v4, v66, v12
	v_mul_f32_e32 v5, v66, v13
	v_mul_f32_e32 v0, v66, v8
	v_mul_f32_e32 v1, v66, v9
	v_mul_f32_e32 v2, v66, v10
	v_mul_f32_e32 v3, v66, v11
	v_mul_f32_e32 v6, v66, v14
	v_mul_f32_e32 v7, v66, v15
	v_cvt_pk_bf16_f32 v0, v0, v1
	v_cvt_pk_bf16_f32 v1, v2, v3
	v_cvt_pk_bf16_f32 v2, v4, v5
	v_cvt_pk_bf16_f32 v3, v6, v7
	v_mul_f32_e32 v4, v66, v52
	v_permlane32_swap_b32_e32 v0, v2
	v_permlane32_swap_b32_e32 v1, v3
	flat_store_dwordx4 v[64:65], v[0:3] offset:32
	v_mul_f32_e32 v5, v66, v53
	v_mul_f32_e32 v6, v66, v54
	v_mul_f32_e32 v0, v66, v48
	v_mul_f32_e32 v1, v66, v49
	v_mul_f32_e32 v2, v66, v50
	v_mul_f32_e32 v3, v66, v51
	v_mul_f32_e32 v7, v66, v55
	v_cvt_pk_bf16_f32 v0, v0, v1
	v_cvt_pk_bf16_f32 v1, v2, v3
	v_cvt_pk_bf16_f32 v2, v4, v5
	v_cvt_pk_bf16_f32 v3, v6, v7
	v_mfma_f32_32x32x16_bf16 v[16:31], v[94:97], v[78:81], v[16:31]
	v_permlane32_swap_b32_e32 v0, v2
	v_permlane32_swap_b32_e32 v1, v3
	flat_store_dwordx4 v[64:65], v[0:3] offset:64
	v_mul_f32_e32 v4, v66, v60
	v_mul_f32_e32 v5, v66, v61
	v_mul_f32_e32 v0, v66, v56
	v_mul_f32_e32 v1, v66, v57
	v_mul_f32_e32 v2, v66, v58
	v_mul_f32_e32 v3, v66, v59
	v_mul_f32_e32 v6, v66, v62
	v_mul_f32_e32 v7, v66, v63
	v_cvt_pk_bf16_f32 v0, v0, v1
	v_cvt_pk_bf16_f32 v1, v2, v3
	v_cvt_pk_bf16_f32 v2, v4, v5
	v_cvt_pk_bf16_f32 v3, v6, v7
	v_mul_f32_e32 v4, v66, v36
	v_permlane32_swap_b32_e32 v0, v2
	v_permlane32_swap_b32_e32 v1, v3
	flat_store_dwordx4 v[64:65], v[0:3] offset:96
	v_mul_f32_e32 v5, v66, v37
	v_mul_f32_e32 v6, v66, v38
	v_mul_f32_e32 v0, v66, v32
	v_mul_f32_e32 v1, v66, v33
	v_mul_f32_e32 v2, v66, v34
	v_mul_f32_e32 v3, v66, v35
	v_mul_f32_e32 v7, v66, v39
	v_cvt_pk_bf16_f32 v0, v0, v1
	v_cvt_pk_bf16_f32 v1, v2, v3
	v_cvt_pk_bf16_f32 v2, v4, v5
	v_cvt_pk_bf16_f32 v3, v6, v7
	v_mul_f32_e32 v4, v66, v44
	v_permlane32_swap_b32_e32 v0, v2
	v_permlane32_swap_b32_e32 v1, v3
	flat_store_dwordx4 v[64:65], v[0:3] offset:128
	v_mul_f32_e32 v5, v66, v45
	v_mul_f32_e32 v6, v66, v46
	v_mul_f32_e32 v0, v66, v40
	v_mul_f32_e32 v1, v66, v41
	v_mul_f32_e32 v2, v66, v42
	v_mul_f32_e32 v3, v66, v43
	v_mul_f32_e32 v7, v66, v47
	v_cvt_pk_bf16_f32 v0, v0, v1
	v_cvt_pk_bf16_f32 v1, v2, v3
	v_cvt_pk_bf16_f32 v2, v4, v5
	v_cvt_pk_bf16_f32 v3, v6, v7
	v_mul_f32_e32 v4, v66, v20
	v_permlane32_swap_b32_e32 v0, v2
	v_permlane32_swap_b32_e32 v1, v3
	flat_store_dwordx4 v[64:65], v[0:3] offset:160
	v_mul_f32_e32 v5, v66, v21
	v_mul_f32_e32 v6, v66, v22
	v_mul_f32_e32 v0, v66, v16
	v_mul_f32_e32 v1, v66, v17
	v_mul_f32_e32 v2, v66, v18
	v_mul_f32_e32 v3, v66, v19
	v_mul_f32_e32 v7, v66, v23
	v_cvt_pk_bf16_f32 v0, v0, v1
	v_cvt_pk_bf16_f32 v1, v2, v3
	v_cvt_pk_bf16_f32 v2, v4, v5
	v_cvt_pk_bf16_f32 v3, v6, v7
	v_mul_f32_e32 v4, v66, v28
	v_permlane32_swap_b32_e32 v0, v2
	v_permlane32_swap_b32_e32 v1, v3
	flat_store_dwordx4 v[64:65], v[0:3] offset:192
	v_mul_f32_e32 v5, v66, v29
	v_mul_f32_e32 v6, v66, v30
	v_mul_f32_e32 v0, v66, v24
	v_mul_f32_e32 v1, v66, v25
	v_mul_f32_e32 v2, v66, v26
	v_mul_f32_e32 v3, v66, v27
	v_mul_f32_e32 v7, v66, v31
	v_cvt_pk_bf16_f32 v0, v0, v1
	v_cvt_pk_bf16_f32 v1, v2, v3
	v_cvt_pk_bf16_f32 v2, v4, v5
	v_cvt_pk_bf16_f32 v3, v6, v7
	s_add_i32 s36, s36, s72
	s_add_i32 s31, s31, s72
	v_permlane32_swap_b32_e32 v0, v2
	v_permlane32_swap_b32_e32 v1, v3
	s_cmpk_gt_i32 s36, 0x1ff
	flat_store_dwordx4 v[64:65], v[0:3] offset:224
	s_setprio 0
	s_waitcnt vmcnt(0) lgkmcnt(0)
	s_barrier
	s_cbranch_scc1 .LBB0_125
.LBB0_114:
	s_cmp_eq_u32 s100, 0
	s_cbranch_scc1 .Lprio_m
	s_setprio 1

; __global__ __launch_bounds__(512, 2) void mega(Params p) {
;     ...
;       for (int rep = 0; rep < REP_DIFF; ++rep)
;       for (int t = blockIdx.x; t < 1024; t += gridDim.x) {
;         int bid = t & 255, rnd = t >> 8, h = bid & 7, qbg = (bid >> 3) + 32 * rnd;
;         int b = qbg / nqb_d, qb = qbg % nqb_d;
;         int ttid = tid; asm volatile("" : "+v"(ttid));
;         long tok0 = (long)b * S, q0 = tok0 + (long)qb * 128;
;         attn_diff_dma((const bf16_t*)(ws + O_DQ) + q0 * 1024 + h * 128, (const bf16_t*)(ws + O_DK) + tok0 * 1024 + h * 128,
;                       (const bf16_t*)(ws + O_DV) + tok0 * 1024 + h * 128, (bf16_t*)(ws + O_ODIFF) + q0 * 1024 + h * 128, S, shm, lam, p.g_sub, ttid);
;       }
.LBB0_127:
	s_or_b64 exec, exec, s[4:5]
	s_add_i32 s40, s40, s72
	s_add_i32 s31, s31, s69
	s_cmpk_gt_i32 s40, 0x3ff
	s_setprio 0
	s_waitcnt lgkmcnt(0)
	s_barrier
	s_cbranch_scc1 .LBB0_141
